# combine_token wave reductions: ds_bpermute shfl_xor chains replaced by DPP adds (quad_perm, row_half_mirror, row_mirror)
# speedup vs baseline: 1.0112x; 1.0039x over previous
.LBB0_1195:
	s_or_b64 exec, exec, s[16:17]
	v_lshlrev_b64 v[76:77], 8, v[62:63]
	s_waitcnt vmcnt(3)
	v_and_b32_e32 v87, 0xffff0000, v89
	v_lshlrev_b32_e32 v86, 16, v89
	v_and_b32_e32 v97, 0xffff0000, v88
	v_lshlrev_b32_e32 v96, 16, v88
	v_and_b32_e32 v89, 0xffff0000, v75
	v_lshlrev_b32_e32 v88, 16, v75
	v_and_b32_e32 v105, 0xffff0000, v74
	v_lshlrev_b32_e32 v104, 16, v74
	v_lshlrev_b64 v[74:75], 1, v[76:77]
	v_lshl_add_u64 v[76:77], v[46:47], 0, v[74:75]
	v_lshl_add_u64 v[74:75], v[48:49], 0, v[74:75]
	global_load_dwordx2 v[76:77], v[76:77], off
	s_nop 0
	global_load_dwordx2 v[78:79], v[74:75], off
	v_lshlrev_b64 v[106:107], 10, v[62:63]
	v_and_b32_e32 v85, 0xffff0000, v91
	v_lshlrev_b32_e32 v84, 16, v91
	v_and_b32_e32 v95, 0xffff0000, v90
	v_lshlrev_b32_e32 v94, 16, v90
	v_and_b32_e32 v91, 0xffff0000, v71
	v_lshlrev_b32_e32 v90, 16, v71
	v_and_b32_e32 v101, 0xffff0000, v70
	v_lshlrev_b32_e32 v100, 16, v70
	s_waitcnt vmcnt(2)
	v_lshlrev_b32_e32 v70, 16, v108
	v_and_b32_e32 v63, 0xffff0000, v109
	v_and_b32_e32 v62, 0xffff0000, v108
	v_lshlrev_b32_e32 v71, 16, v109
	v_lshl_add_u64 v[106:107], v[106:107], 1, v[54:55]
	v_and_b32_e32 v99, 0xffff0000, v66
	v_lshlrev_b32_e32 v98, 16, v66
	v_lshlrev_b64 v[114:115], 2, v[50:51]
	v_pk_add_f32 v[96:97], v[96:97], v[98:99] neg_lo:[0,1] neg_hi:[0,1]
	v_pk_add_f32 v[94:95], v[94:95], v[98:99] neg_lo:[0,1] neg_hi:[0,1]
	v_pk_fma_f32 v[14:15], v[96:97], v[14:15], v[98:99]
	v_and_b32_e32 v103, 0xffff0000, v72
	v_pk_fma_f32 v[10:11], v[94:95], v[10:11], v[14:15]
	v_lshlrev_b32_e32 v102, 16, v72
	v_pk_add_f32 v[14:15], v[102:103], v[104:105] neg_lo:[0,1] neg_hi:[0,1]
	v_and_b32_e32 v83, 0xffff0000, v67
	v_pk_fma_f32 v[6:7], v[14:15], v[6:7], v[104:105]
	v_pk_add_f32 v[14:15], v[100:101], v[104:105] neg_lo:[0,1] neg_hi:[0,1]
	v_lshlrev_b32_e32 v82, 16, v67
	v_pk_fma_f32 v[2:3], v[14:15], v[2:3], v[6:7]
	v_and_b32_e32 v93, 0xffff0000, v73
	v_lshlrev_b32_e32 v92, 16, v73
	v_lshlrev_b32_e32 v73, 16, v69
	v_lshlrev_b32_e32 v72, 16, v68
	v_and_b32_e32 v67, 0xffff0000, v81
	v_and_b32_e32 v66, 0xffff0000, v80
	v_and_b32_e32 v69, 0xffff0000, v69
	v_and_b32_e32 v68, 0xffff0000, v68
	s_waitcnt vmcnt(1)
	v_lshlrev_b32_e32 v75, 16, v77
	v_lshlrev_b32_e32 v74, 16, v76
	s_waitcnt vmcnt(0)
	v_lshlrev_b32_e32 v109, 16, v79
	v_lshlrev_b32_e32 v108, 16, v78
	v_pk_add_f32 v[74:75], v[74:75], v[108:109]
	global_load_dwordx2 v[108:109], v[106:107], off offset:512
	s_nop 0
	global_load_dwordx2 v[106:107], v[106:107], off offset:1536
	s_load_dwordx8 s[44:51], s[52:53], 0x108
	v_and_b32_e32 v77, 0xffff0000, v77
	v_and_b32_e32 v76, 0xffff0000, v76
	v_and_b32_e32 v79, 0xffff0000, v79
	v_and_b32_e32 v78, 0xffff0000, v78
	s_waitcnt lgkmcnt(0)
	v_lshl_add_u64 v[116:117], s[44:45], 0, v[114:115]
	global_load_dwordx4 v[94:97], v[116:117], off
	v_lshl_add_u64 v[118:119], s[46:47], 0, v[114:115]
	global_load_dwordx4 v[98:101], v[118:119], off
	v_pk_add_f32 v[76:77], v[76:77], v[78:79]
	s_waitcnt vmcnt(3)
	v_lshlrev_b32_e32 v110, 16, v108
	v_add_f32_e32 v0, v74, v76
	v_add_f32_e32 v0, v0, v75
	v_add_f32_e32 v0, v77, v0
	v_and_b32_e32 v111, 0xffff0000, v108
	s_waitcnt vmcnt(2)
	v_lshlrev_b32_e32 v112, 16, v106
	v_and_b32_e32 v113, 0xffff0000, v106
	v_pk_add_f32 v[6:7], v[110:111], v[112:113]
	s_waitcnt lgkmcnt(0)
	s_nop 1
	v_add_f32_dpp v0, v0, v0 quad_perm:[1,0,3,2] row_mask:0xf bank_mask:0xf bound_ctrl:1
	v_pk_add_f32 v[6:7], v[6:7], -2.0 op_sel_hi:[1,0]
	v_lshlrev_b32_e32 v108, 16, v109
	s_waitcnt vmcnt(1)
	v_pk_fma_f32 v[6:7], v[6:7], v[94:95], 2.0 op_sel_hi:[1,1,0]
	v_and_b32_e32 v109, 0xffff0000, v109
	s_waitcnt lgkmcnt(0)
	s_nop 1
	v_add_f32_dpp v0, v0, v0 quad_perm:[2,3,0,1] row_mask:0xf bank_mask:0xf bound_ctrl:1
	v_pk_mul_f32 v[6:7], v[10:11], v[6:7]
	v_lshlrev_b32_e32 v106, 16, v107
	v_pk_mul_f32 v[2:3], v[2:3], v[6:7]
	v_pk_add_f32 v[6:7], v[84:85], v[82:83] neg_lo:[0,1] neg_hi:[0,1]
	s_waitcnt lgkmcnt(0)
	s_nop 1
	v_add_f32_dpp v0, v0, v0 row_half_mirror row_mask:0xf bank_mask:0xf bound_ctrl:1
	s_waitcnt vmcnt(0)
	v_pk_mul_f32 v[2:3], v[98:99], v[2:3]
	v_and_b32_e32 v107, 0xffff0000, v107
	s_waitcnt lgkmcnt(0)
	s_nop 1
	v_add_f32_dpp v0, v0, v0 row_mirror row_mask:0xf bank_mask:0xf bound_ctrl:1
	v_mul_f32_e32 v78, 0x3c800000, v0
	v_add_f32_e32 v0, 0, v2
	v_add_f32_e32 v0, v0, v3
	v_pk_add_f32 v[2:3], v[86:87], v[82:83] neg_lo:[0,1] neg_hi:[0,1]
	s_nop 0
	v_pk_fma_f32 v[2:3], v[2:3], v[16:17], v[82:83]
	global_load_dwordx4 v[14:17], v[44:45], off
	v_pk_fma_f32 v[2:3], v[6:7], v[12:13], v[2:3]
	v_pk_add_f32 v[6:7], v[92:93], v[88:89] neg_lo:[0,1] neg_hi:[0,1]
	s_nop 0
	v_pk_fma_f32 v[6:7], v[6:7], v[8:9], v[88:89]
	v_pk_add_f32 v[8:9], v[90:91], v[88:89] neg_lo:[0,1] neg_hi:[0,1]
	s_nop 0
	v_pk_fma_f32 v[4:5], v[8:9], v[4:5], v[6:7]
	global_load_dwordx4 v[8:11], v[36:37], off offset:2048
	v_pk_add_f32 v[6:7], v[108:109], v[106:107]
	s_waitcnt vmcnt(0)
	v_mov_b32_e32 v12, v8
	v_pk_add_f32 v[6:7], v[6:7], -2.0 op_sel_hi:[1,0]
	v_mov_b32_e32 v13, v10
	v_pk_fma_f32 v[6:7], v[6:7], v[96:97], 2.0 op_sel_hi:[1,1,0]
	v_mov_b32_e32 v10, v9
	v_pk_mul_f32 v[2:3], v[2:3], v[6:7]
	v_pk_add_f32 v[8:9], v[68:69], v[62:63] neg_lo:[0,1] neg_hi:[0,1]
	v_pk_mul_f32 v[2:3], v[4:5], v[2:3]
	v_lshlrev_b32_e32 v5, 16, v81
	v_lshlrev_b32_e32 v4, 16, v80
	v_pk_add_f32 v[4:5], v[4:5], v[70:71] neg_lo:[0,1] neg_hi:[0,1]
	v_pk_mul_f32 v[2:3], v[100:101], v[2:3]
	v_pk_fma_f32 v[4:5], v[4:5], v[12:13], v[70:71]
	v_pk_add_f32 v[12:13], v[72:73], v[70:71] neg_lo:[0,1] neg_hi:[0,1]
	v_mov_b32_e32 v70, v14
	v_mov_b32_e32 v71, v16
	v_pk_fma_f32 v[12:13], v[12:13], v[70:71], v[4:5]
	v_pk_add_f32 v[4:5], v[66:67], v[62:63] neg_lo:[0,1] neg_hi:[0,1]
	v_mov_b32_e32 v16, v15
	v_pk_fma_f32 v[4:5], v[4:5], v[10:11], v[62:63]
	v_pk_add_f32 v[14:15], v[76:77], v[78:79] op_sel_hi:[1,0] neg_lo:[0,1] neg_hi:[0,1]
	v_pk_fma_f32 v[10:11], v[8:9], v[16:17], v[4:5]
	v_pk_add_f32 v[4:5], v[74:75], v[78:79] op_sel_hi:[1,0] neg_lo:[0,1] neg_hi:[0,1]
	v_mov_b32_e32 v9, v14
	v_mov_b32_e32 v8, v4
	v_pk_mul_f32 v[8:9], v[8:9], v[8:9]
	v_mov_b32_e32 v16, v15
	v_mov_b32_e32 v17, v5
	v_pk_mul_f32 v[16:17], v[16:17], v[16:17]
	v_add_f32_e32 v8, v8, v9
	v_add_f32_e32 v8, v17, v8
	v_add_f32_e32 v8, v16, v8
	v_add_f32_e32 v0, v0, v2
	v_add_f32_e32 v0, v0, v3
	v_lshl_add_u64 v[6:7], s[50:51], 0, v[114:115]
	s_waitcnt lgkmcnt(0)
	s_nop 1
	v_add_f32_dpp v8, v8, v8 quad_perm:[1,0,3,2] row_mask:0xf bank_mask:0xf bound_ctrl:1
	s_waitcnt lgkmcnt(0)
	s_nop 1
	v_add_f32_dpp v0, v0, v0 quad_perm:[1,0,3,2] row_mask:0xf bank_mask:0xf bound_ctrl:1
	s_waitcnt lgkmcnt(0)
	s_nop 1
	v_add_f32_dpp v8, v8, v8 quad_perm:[2,3,0,1] row_mask:0xf bank_mask:0xf bound_ctrl:1
	s_waitcnt lgkmcnt(0)
	s_nop 1
	v_add_f32_dpp v0, v0, v0 quad_perm:[2,3,0,1] row_mask:0xf bank_mask:0xf bound_ctrl:1
	s_waitcnt lgkmcnt(0)
	s_nop 1
	v_add_f32_dpp v8, v8, v8 row_half_mirror row_mask:0xf bank_mask:0xf bound_ctrl:1
	s_waitcnt lgkmcnt(0)
	s_nop 1
	v_add_f32_dpp v0, v0, v0 row_half_mirror row_mask:0xf bank_mask:0xf bound_ctrl:1
	s_waitcnt lgkmcnt(0)
	s_nop 1
	v_add_f32_dpp v8, v8, v8 row_mirror row_mask:0xf bank_mask:0xf bound_ctrl:1
	v_fmamk_f32 v8, v8, 0x3c800000, v180
	v_cmp_gt_f32_e32 vcc, s27, v8
	v_mul_f32_e32 v9, 0x4b800000, v8
	s_waitcnt lgkmcnt(0)
	s_nop 1
	v_add_f32_dpp v0, v0, v0 row_mirror row_mask:0xf bank_mask:0xf bound_ctrl:1
	v_cndmask_b32_e32 v8, v8, v9, vcc
	v_rsq_f32_e32 v8, v8
	v_lshl_add_u64 v[2:3], s[48:49], 0, v[114:115]
	v_mul_f32_e32 v9, 0x45800000, v8
	v_cndmask_b32_e32 v16, v8, v9, vcc
	v_pk_mul_f32 v[62:63], v[4:5], v[16:17] op_sel_hi:[1,0]
	global_load_dwordx4 v[2:5], v[2:3], off
	v_pk_mul_f32 v[14:15], v[14:15], v[16:17] op_sel_hi:[1,0]
	global_load_dwordx4 v[6:9], v[6:7], off
	s_waitcnt vmcnt(1)
	v_mov_b32_e32 v67, v4
	v_mov_b32_e32 v4, v3
	s_waitcnt vmcnt(0)
	v_mov_b32_e32 v69, v8
	v_mov_b32_e32 v8, v7
	v_mov_b32_e32 v66, v2
	v_mov_b32_e32 v68, v6
	v_pk_fma_f32 v[2:3], v[14:15], v[4:5], v[8:9]
	v_pk_fma_f32 v[62:63], v[62:63], v[66:67], v[68:69]
	v_pk_fma_f32 v[2:3], v[10:11], v[0:1], v[2:3] op_sel_hi:[1,0,1]
	v_pk_fma_f32 v[12:13], v[12:13], v[0:1], v[62:63] op_sel_hi:[1,0,1]
	v_pk_mul_f32 v[2:3], v[58:59], v[2:3]
	v_pk_mul_f32 v[12:13], v[60:61], v[12:13]
	v_and_b32_sdwa v5, v3, v177 dst_sel:DWORD dst_unused:UNUSED_PAD src0_sel:WORD_1 src1_sel:DWORD
	v_and_b32_sdwa v6, v2, v177 dst_sel:DWORD dst_unused:UNUSED_PAD src0_sel:WORD_1 src1_sel:DWORD
	v_and_b32_sdwa v0, v13, v177 dst_sel:DWORD dst_unused:UNUSED_PAD src0_sel:WORD_1 src1_sel:DWORD
	v_and_b32_sdwa v4, v12, v177 dst_sel:DWORD dst_unused:UNUSED_PAD src0_sel:WORD_1 src1_sel:DWORD
	v_add3_u32 v3, v3, v5, s28
	v_add3_u32 v2, v2, v6, s28
	v_add3_u32 v4, v12, v4, s28
	v_add3_u32 v0, v13, v0, s28
	v_and_b32_e32 v3, 0xffff0000, v3
	v_and_b32_e32 v2, 0xffff0000, v2
	v_or_b32_sdwa v3, v3, v0 dst_sel:DWORD dst_unused:UNUSED_PAD src0_sel:DWORD src1_sel:WORD_1
	v_or_b32_sdwa v2, v2, v4 dst_sel:DWORD dst_unused:UNUSED_PAD src0_sel:DWORD src1_sel:WORD_1
	global_store_dwordx2 v[64:65], v[2:3], off offset:1536

.Lgate_loop:
	v_lshl_add_u64 v[248:249], v[2:3], 0, s[38:39]
	v_lshl_add_u64 v[248:249], v[248:249], 0, s[38:39]
	v_lshl_add_u64 v[198:199], v[248:249], 0, s[38:39]
	v_lshl_add_u64 v[198:199], v[198:199], 0, s[38:39]
	global_load_dwordx4 v[136:139], v[2:3], off offset:-2048
	global_load_dwordx4 v[140:143], v[2:3], off offset:-1024
	global_load_dwordx4 v[144:147], v[2:3], off
	global_load_dwordx4 v[148:151], v[2:3], off offset:1024
	global_load_dwordx4 v[152:155], v[2:3], off offset:2048
	global_load_dwordx4 v[156:159], v[2:3], off offset:3072
	global_load_dwordx4 v[160:163], v[248:249], off offset:-4096
	global_load_dwordx4 v[164:167], v[248:249], off offset:-3072
	global_load_dwordx4 v[168:171], v[248:249], off offset:-2048
	global_load_dwordx4 v[204:207], v[248:249], off offset:-1024
	global_load_dwordx4 v[212:215], v[248:249], off
	global_load_dwordx4 v[216:219], v[248:249], off offset:1024
	global_load_dwordx4 v[220:223], v[248:249], off offset:2048
	global_load_dwordx4 v[224:227], v[248:249], off offset:3072
	global_load_dwordx4 v[228:231], v[198:199], off offset:-4096
	global_load_dwordx4 v[232:235], v[198:199], off offset:-3072
	v_add_u32_e32 v0, s6, v33
	ds_read_b128 v[8:11], v0
	ds_read_b128 v[12:15], v0 offset:256
	ds_read_b128 v[236:239], v0 offset:512
	v_mov_b64_e32 v[2:3], v[198:199]
	s_add_i32 s6, s6, 64
	ds_read_b128 v[240:243], v0 offset:16
	ds_read_b128 v[244:247], v0 offset:272
	ds_read_b128 v[184:187], v0 offset:528
	s_waitcnt vmcnt(12)
	s_waitcnt lgkmcnt(3)
	v_pk_fma_f32 v[76:77], v[8:9], v[136:137], v[76:77] op_sel_hi:[0,1,1]
	v_pk_fma_f32 v[74:75], v[8:9], v[138:139], v[74:75] op_sel_hi:[0,1,1]
	v_pk_fma_f32 v[70:71], v[12:13], v[136:137], v[70:71] op_sel_hi:[0,1,1]
	v_pk_fma_f32 v[68:69], v[12:13], v[138:139], v[68:69] op_sel_hi:[0,1,1]
	v_pk_fma_f32 v[60:61], v[236:237], v[136:137], v[60:61] op_sel_hi:[0,1,1]
	v_pk_fma_f32 v[58:59], v[236:237], v[138:139], v[58:59] op_sel_hi:[0,1,1]
	v_pk_fma_f32 v[76:77], v[8:9], v[140:141], v[76:77] op_sel:[1,0,0]
	v_pk_fma_f32 v[74:75], v[8:9], v[142:143], v[74:75] op_sel:[1,0,0]
	v_pk_fma_f32 v[70:71], v[12:13], v[140:141], v[70:71] op_sel:[1,0,0]
	v_pk_fma_f32 v[68:69], v[12:13], v[142:143], v[68:69] op_sel:[1,0,0]
	v_pk_fma_f32 v[60:61], v[236:237], v[140:141], v[60:61] op_sel:[1,0,0]
	v_pk_fma_f32 v[58:59], v[236:237], v[142:143], v[58:59] op_sel:[1,0,0]
	v_pk_fma_f32 v[76:77], v[10:11], v[144:145], v[76:77] op_sel_hi:[0,1,1]
	v_pk_fma_f32 v[74:75], v[10:11], v[146:147], v[74:75] op_sel_hi:[0,1,1]
	v_pk_fma_f32 v[70:71], v[14:15], v[144:145], v[70:71] op_sel_hi:[0,1,1]
	v_pk_fma_f32 v[68:69], v[14:15], v[146:147], v[68:69] op_sel_hi:[0,1,1]
	v_pk_fma_f32 v[60:61], v[238:239], v[144:145], v[60:61] op_sel_hi:[0,1,1]
	v_pk_fma_f32 v[58:59], v[238:239], v[146:147], v[58:59] op_sel_hi:[0,1,1]
	v_pk_fma_f32 v[76:77], v[10:11], v[148:149], v[76:77] op_sel:[1,0,0]
	v_pk_fma_f32 v[74:75], v[10:11], v[150:151], v[74:75] op_sel:[1,0,0]
	v_pk_fma_f32 v[70:71], v[14:15], v[148:149], v[70:71] op_sel:[1,0,0]
	v_pk_fma_f32 v[68:69], v[14:15], v[150:151], v[68:69] op_sel:[1,0,0]
	v_pk_fma_f32 v[60:61], v[238:239], v[148:149], v[60:61] op_sel:[1,0,0]
	v_pk_fma_f32 v[58:59], v[238:239], v[150:151], v[58:59] op_sel:[1,0,0]
	ds_read_b128 v[8:11], v0 offset:32
	ds_read_b128 v[12:15], v0 offset:288
	ds_read_b128 v[236:239], v0 offset:544
	s_waitcnt vmcnt(8)
	s_waitcnt lgkmcnt(3)
	v_pk_fma_f32 v[76:77], v[240:241], v[152:153], v[76:77] op_sel_hi:[0,1,1]
	v_pk_fma_f32 v[74:75], v[240:241], v[154:155], v[74:75] op_sel_hi:[0,1,1]
	v_pk_fma_f32 v[70:71], v[244:245], v[152:153], v[70:71] op_sel_hi:[0,1,1]
	v_pk_fma_f32 v[68:69], v[244:245], v[154:155], v[68:69] op_sel_hi:[0,1,1]
	v_pk_fma_f32 v[60:61], v[184:185], v[152:153], v[60:61] op_sel_hi:[0,1,1]
	v_pk_fma_f32 v[58:59], v[184:185], v[154:155], v[58:59] op_sel_hi:[0,1,1]
	v_pk_fma_f32 v[76:77], v[240:241], v[156:157], v[76:77] op_sel:[1,0,0]
	v_pk_fma_f32 v[74:75], v[240:241], v[158:159], v[74:75] op_sel:[1,0,0]
	v_pk_fma_f32 v[70:71], v[244:245], v[156:157], v[70:71] op_sel:[1,0,0]
	v_pk_fma_f32 v[68:69], v[244:245], v[158:159], v[68:69] op_sel:[1,0,0]
	v_pk_fma_f32 v[60:61], v[184:185], v[156:157], v[60:61] op_sel:[1,0,0]
	v_pk_fma_f32 v[58:59], v[184:185], v[158:159], v[58:59] op_sel:[1,0,0]
	v_pk_fma_f32 v[76:77], v[242:243], v[160:161], v[76:77] op_sel_hi:[0,1,1]
	v_pk_fma_f32 v[74:75], v[242:243], v[162:163], v[74:75] op_sel_hi:[0,1,1]
	v_pk_fma_f32 v[70:71], v[246:247], v[160:161], v[70:71] op_sel_hi:[0,1,1]
	v_pk_fma_f32 v[68:69], v[246:247], v[162:163], v[68:69] op_sel_hi:[0,1,1]
	v_pk_fma_f32 v[60:61], v[186:187], v[160:161], v[60:61] op_sel_hi:[0,1,1]
	v_pk_fma_f32 v[58:59], v[186:187], v[162:163], v[58:59] op_sel_hi:[0,1,1]
	v_pk_fma_f32 v[76:77], v[242:243], v[164:165], v[76:77] op_sel:[1,0,0]
	v_pk_fma_f32 v[74:75], v[242:243], v[166:167], v[74:75] op_sel:[1,0,0]
	v_pk_fma_f32 v[70:71], v[246:247], v[164:165], v[70:71] op_sel:[1,0,0]
	v_pk_fma_f32 v[68:69], v[246:247], v[166:167], v[68:69] op_sel:[1,0,0]
	v_pk_fma_f32 v[60:61], v[186:187], v[164:165], v[60:61] op_sel:[1,0,0]
	v_pk_fma_f32 v[58:59], v[186:187], v[166:167], v[58:59] op_sel:[1,0,0]
	ds_read_b128 v[240:243], v0 offset:48
	ds_read_b128 v[244:247], v0 offset:304
	ds_read_b128 v[184:187], v0 offset:560
	s_waitcnt vmcnt(4)
	s_waitcnt lgkmcnt(3)
	v_pk_fma_f32 v[76:77], v[8:9], v[168:169], v[76:77] op_sel_hi:[0,1,1]
	v_pk_fma_f32 v[74:75], v[8:9], v[170:171], v[74:75] op_sel_hi:[0,1,1]
	v_pk_fma_f32 v[70:71], v[12:13], v[168:169], v[70:71] op_sel_hi:[0,1,1]
	v_pk_fma_f32 v[68:69], v[12:13], v[170:171], v[68:69] op_sel_hi:[0,1,1]
	v_pk_fma_f32 v[60:61], v[236:237], v[168:169], v[60:61] op_sel_hi:[0,1,1]
	v_pk_fma_f32 v[58:59], v[236:237], v[170:171], v[58:59] op_sel_hi:[0,1,1]
	v_pk_fma_f32 v[76:77], v[8:9], v[204:205], v[76:77] op_sel:[1,0,0]
	v_pk_fma_f32 v[74:75], v[8:9], v[206:207], v[74:75] op_sel:[1,0,0]
	v_pk_fma_f32 v[70:71], v[12:13], v[204:205], v[70:71] op_sel:[1,0,0]
	v_pk_fma_f32 v[68:69], v[12:13], v[206:207], v[68:69] op_sel:[1,0,0]
	v_pk_fma_f32 v[60:61], v[236:237], v[204:205], v[60:61] op_sel:[1,0,0]
	v_pk_fma_f32 v[58:59], v[236:237], v[206:207], v[58:59] op_sel:[1,0,0]
	v_pk_fma_f32 v[76:77], v[10:11], v[212:213], v[76:77] op_sel_hi:[0,1,1]
	v_pk_fma_f32 v[74:75], v[10:11], v[214:215], v[74:75] op_sel_hi:[0,1,1]
	v_pk_fma_f32 v[70:71], v[14:15], v[212:213], v[70:71] op_sel_hi:[0,1,1]
	v_pk_fma_f32 v[68:69], v[14:15], v[214:215], v[68:69] op_sel_hi:[0,1,1]
	v_pk_fma_f32 v[60:61], v[238:239], v[212:213], v[60:61] op_sel_hi:[0,1,1]
	v_pk_fma_f32 v[58:59], v[238:239], v[214:215], v[58:59] op_sel_hi:[0,1,1]
	v_pk_fma_f32 v[76:77], v[10:11], v[216:217], v[76:77] op_sel:[1,0,0]
	v_pk_fma_f32 v[74:75], v[10:11], v[218:219], v[74:75] op_sel:[1,0,0]
	v_pk_fma_f32 v[70:71], v[14:15], v[216:217], v[70:71] op_sel:[1,0,0]
	v_pk_fma_f32 v[68:69], v[14:15], v[218:219], v[68:69] op_sel:[1,0,0]
	v_pk_fma_f32 v[60:61], v[238:239], v[216:217], v[60:61] op_sel:[1,0,0]
	v_pk_fma_f32 v[58:59], v[238:239], v[218:219], v[58:59] op_sel:[1,0,0]
	s_waitcnt vmcnt(0)
	s_waitcnt lgkmcnt(0)
	v_pk_fma_f32 v[76:77], v[240:241], v[220:221], v[76:77] op_sel_hi:[0,1,1]
	v_pk_fma_f32 v[74:75], v[240:241], v[222:223], v[74:75] op_sel_hi:[0,1,1]
	v_pk_fma_f32 v[70:71], v[244:245], v[220:221], v[70:71] op_sel_hi:[0,1,1]
	v_pk_fma_f32 v[68:69], v[244:245], v[222:223], v[68:69] op_sel_hi:[0,1,1]
	v_pk_fma_f32 v[60:61], v[184:185], v[220:221], v[60:61] op_sel_hi:[0,1,1]
	v_pk_fma_f32 v[58:59], v[184:185], v[222:223], v[58:59] op_sel_hi:[0,1,1]
	v_pk_fma_f32 v[76:77], v[240:241], v[224:225], v[76:77] op_sel:[1,0,0]
	v_pk_fma_f32 v[74:75], v[240:241], v[226:227], v[74:75] op_sel:[1,0,0]
	v_pk_fma_f32 v[70:71], v[244:245], v[224:225], v[70:71] op_sel:[1,0,0]
	v_pk_fma_f32 v[68:69], v[244:245], v[226:227], v[68:69] op_sel:[1,0,0]
	v_pk_fma_f32 v[60:61], v[184:185], v[224:225], v[60:61] op_sel:[1,0,0]
	v_pk_fma_f32 v[58:59], v[184:185], v[226:227], v[58:59] op_sel:[1,0,0]
	v_pk_fma_f32 v[76:77], v[242:243], v[228:229], v[76:77] op_sel_hi:[0,1,1]
	v_pk_fma_f32 v[74:75], v[242:243], v[230:231], v[74:75] op_sel_hi:[0,1,1]
	v_pk_fma_f32 v[70:71], v[246:247], v[228:229], v[70:71] op_sel_hi:[0,1,1]
	v_pk_fma_f32 v[68:69], v[246:247], v[230:231], v[68:69] op_sel_hi:[0,1,1]
	v_pk_fma_f32 v[60:61], v[186:187], v[228:229], v[60:61] op_sel_hi:[0,1,1]
	v_pk_fma_f32 v[58:59], v[186:187], v[230:231], v[58:59] op_sel_hi:[0,1,1]
	v_pk_fma_f32 v[76:77], v[242:243], v[232:233], v[76:77] op_sel:[1,0,0]
	v_pk_fma_f32 v[74:75], v[242:243], v[234:235], v[74:75] op_sel:[1,0,0]
	v_pk_fma_f32 v[70:71], v[246:247], v[232:233], v[70:71] op_sel:[1,0,0]
	v_pk_fma_f32 v[68:69], v[246:247], v[234:235], v[68:69] op_sel:[1,0,0]
	v_pk_fma_f32 v[60:61], v[186:187], v[232:233], v[60:61] op_sel:[1,0,0]
	v_pk_fma_f32 v[58:59], v[186:187], v[234:235], v[58:59] op_sel:[1,0,0]
	s_cmpk_lg_i32 s6, 0x100
	s_cbranch_scc1 .Lgate_loop
	v_swap_b32 v77, v74
	v_swap_b32 v71, v68
	v_swap_b32 v61, v58
	v_cmp_gt_i32_e32 vcc, s11, v18
	v_lshlrev_b32_e32 v35, 2, v32
	v_lshlrev_b32_e32 v72, 1, v20
	v_lshlrev_b32_e32 v66, 1, v34
	s_and_saveexec_b64 s[14:15], vcc
	s_cbranch_execz .LBB0_1226
	v_ashrrev_i32_e32 v19, 31, v18
	v_lshlrev_b64 v[2:3], 9, v[18:19]
	v_lshl_add_u64 v[4:5], v[28:29], 0, v[2:3]
	v_lshl_add_u64 v[2:3], v[30:31], 0, v[2:3]
	global_load_dwordx2 v[8:9], v[4:5], off
	global_load_dwordx2 v[10:11], v[2:3], off
	v_mov_b64_e32 v[6:7], s[56:57]
	v_mad_i64_i32 v[80:81], s[6:7], v18, s24, v[6:7]
	v_mov_b32_e32 v73, v1
	s_load_dwordx2 s[6:7], s[52:53], 0xc8
	v_lshl_add_u64 v[2:3], v[80:81], 0, v[72:73]
	s_movk_i32 s2, 0x1000
	v_add_co_u32_e32 v2, vcc, s2, v2
	v_readlane_b32 s2, v255, 55
	v_readlane_b32 s3, v255, 56
	s_lshl_b64 s[12:13], s[2:3], 2
	s_waitcnt lgkmcnt(0)
	s_add_u32 s6, s6, s12
	v_addc_co_u32_e32 v3, vcc, 0, v3, vcc
	s_addc_u32 s7, s7, s13
	global_load_dwordx2 v[12:13], v[2:3], off offset:512
	v_add_u32_e32 v73, -1, v18
	global_load_dwordx4 v[2:5], v35, s[6:7]
	v_mov_b32_e32 v67, v1
	v_mad_i64_i32 v[88:89], s[6:7], v73, s24, v[6:7]
	v_lshl_add_u64 v[6:7], v[80:81], 0, v[66:67]
	global_load_dwordx2 v[86:87], v[6:7], off
	v_cmp_lt_i32_e64 s[44:45], v188, v182
	v_cmp_gt_i32_e32 vcc, s93, v18
	v_mov_b32_e32 v82, 0
	v_cndmask_b32_e64 v14, v181, v188, s[44:45]
	v_cmp_lt_i32_e64 s[44:45], v191, v182
	v_lshlrev_b32_e32 v65, 2, v14
	v_cndmask_b32_e32 v0, v252, v202, vcc
	v_cndmask_b32_e64 v15, v181, v191, s[44:45]
	v_lshlrev_b32_e32 v63, 2, v15
	v_lshlrev_b64 v[14:15], 11, v[18:19]
	v_cmp_lt_i32_e64 s[44:45], v190, v182
	v_lshl_add_u64 v[78:79], v[52:53], 0, v[14:15]
	v_and_b32_e32 v0, v0, v18
	v_cndmask_b32_e64 v16, v181, v190, s[44:45]
	v_cmp_lt_i32_e64 s[44:45], v189, v182
	v_lshlrev_b32_e32 v43, 2, v16
	v_mov_b32_e32 v84, 0
	v_cndmask_b32_e64 v17, v181, v189, s[44:45]
	v_lshlrev_b32_e32 v39, 2, v17
	v_cmp_ne_u32_e64 s[44:45], 0, v0
	s_waitcnt vmcnt(4)
	v_lshlrev_b32_e32 v7, 16, v9
	v_lshlrev_b32_e32 v6, 16, v8
	s_waitcnt vmcnt(3)
	v_lshlrev_b32_e32 v15, 16, v11
	v_lshlrev_b32_e32 v14, 16, v10
	v_and_b32_e32 v9, 0xffff0000, v9
	v_and_b32_e32 v8, 0xffff0000, v8
	v_and_b32_e32 v11, 0xffff0000, v11
	v_and_b32_e32 v10, 0xffff0000, v10
	v_pk_add_f32 v[6:7], v[6:7], v[14:15]
	v_pk_add_f32 v[8:9], v[8:9], v[10:11]
	v_mov_b32_e32 v14, v6
	v_mov_b32_e32 v15, v8
	v_mov_b32_e32 v16, v9
	v_mov_b32_e32 v17, v7
	v_pk_mul_f32 v[14:15], v[14:15], v[14:15]
	v_pk_mul_f32 v[16:17], v[16:17], v[16:17]
	v_add_f32_e32 v14, v14, v15
	v_add_f32_e32 v14, v14, v17
	v_add_f32_e32 v14, v16, v14
	s_waitcnt vmcnt(2)
	v_lshlrev_b32_e32 v11, 16, v13
	v_lshlrev_b32_e32 v10, 16, v12
	v_and_b32_e32 v13, 0xffff0000, v13
	v_and_b32_e32 v12, 0xffff0000, v12
	s_waitcnt lgkmcnt(0)
	s_nop 1
	v_add_f32_dpp v85, v14, v14 quad_perm:[1,0,3,2] row_mask:0xf bank_mask:0xf bound_ctrl:1
	s_waitcnt vmcnt(1)
	v_mov_b32_e32 v14, v2
	v_mov_b32_e32 v15, v4
	v_mul_f32_e32 v73, 0xbfb8aa3b, v10
	v_mul_f32_e32 v83, 0xbfb8aa3b, v12
	s_waitcnt lgkmcnt(0)
	s_nop 1
	v_add_f32_dpp v2, v85, v85 quad_perm:[2,3,0,1] row_mask:0xf bank_mask:0xf bound_ctrl:1
	v_mul_f32_e32 v16, 0xbfb8aa3b, v11
	v_mul_f32_e32 v17, 0xbfb8aa3b, v13
	v_exp_f32_e32 v73, v73
	v_exp_f32_e32 v83, v83
	s_waitcnt lgkmcnt(0)
	s_nop 1
	v_add_f32_dpp v2, v2, v2 row_half_mirror row_mask:0xf bank_mask:0xf bound_ctrl:1
	v_exp_f32_e32 v16, v16
	v_exp_f32_e32 v17, v17
	v_add_f32_e32 v73, 1.0, v73
	v_add_f32_e32 v83, 1.0, v83
	s_waitcnt lgkmcnt(0)
	s_nop 1
	v_add_f32_dpp v2, v2, v2 row_mirror row_mask:0xf bank_mask:0xf bound_ctrl:1
	v_fmamk_f32 v2, v2, 0x3c800000, v174
	v_mul_f32_e32 v4, 0x4b800000, v2
	v_cmp_gt_f32_e64 s[46:47], s27, v2
	v_add_f32_e32 v85, 1.0, v16
	v_add_f32_e32 v91, 1.0, v17
	v_cndmask_b32_e64 v2, v2, v4, s[46:47]
	v_rcp_f32_e32 v16, v73
	v_rcp_f32_e32 v90, v83
	v_rcp_f32_e32 v17, v85
	v_rcp_f32_e32 v91, v91
	v_rsq_f32_e32 v73, v2
	v_mov_b32_e32 v4, v3
	v_pk_mul_f32 v[2:3], v[16:17], v[10:11]
	v_pk_mul_f32 v[10:11], v[90:91], v[12:13]
	v_mul_f32_e32 v12, 0x45800000, v73
	v_cndmask_b32_e64 v12, v73, v12, s[46:47]
	v_pk_mul_f32 v[8:9], v[8:9], v[12:13] op_sel_hi:[1,0]
	v_pk_mul_f32 v[6:7], v[6:7], v[12:13] op_sel_hi:[1,0]
	v_pk_mul_f32 v[4:5], v[4:5], v[8:9]
	v_pk_mul_f32 v[6:7], v[14:15], v[6:7]
	v_pk_mul_f32 v[4:5], v[10:11], v[4:5]
	v_pk_mul_f32 v[2:3], v[2:3], v[6:7]
	v_and_b32_sdwa v8, v5, v177 dst_sel:DWORD dst_unused:UNUSED_PAD src0_sel:WORD_1 src1_sel:DWORD
	v_and_b32_sdwa v9, v4, v177 dst_sel:DWORD dst_unused:UNUSED_PAD src0_sel:WORD_1 src1_sel:DWORD
	v_and_b32_sdwa v6, v3, v177 dst_sel:DWORD dst_unused:UNUSED_PAD src0_sel:WORD_1 src1_sel:DWORD
	v_and_b32_sdwa v7, v2, v177 dst_sel:DWORD dst_unused:UNUSED_PAD src0_sel:WORD_1 src1_sel:DWORD
	v_add3_u32 v5, v5, v8, s28
	v_add3_u32 v4, v4, v9, s28
	v_add3_u32 v2, v2, v7, s28
	v_add3_u32 v3, v3, v6, s28
	v_and_b32_e32 v5, 0xffff0000, v5
	v_and_b32_e32 v4, 0xffff0000, v4
	v_or_b32_sdwa v3, v5, v3 dst_sel:DWORD dst_unused:UNUSED_PAD src0_sel:DWORD src1_sel:WORD_1
	v_or_b32_sdwa v2, v4, v2 dst_sel:DWORD dst_unused:UNUSED_PAD src0_sel:DWORD src1_sel:WORD_1
	v_mov_b32_e32 v85, 0
	global_store_dwordx2 v[78:79], v[2:3], off offset:1024
	s_and_saveexec_b64 s[16:17], s[44:45]
	s_cbranch_execz .LBB0_1214
	v_lshl_add_u64 v[2:3], v[88:89], 0, v[66:67]
	global_load_dwordx2 v[84:85], v[2:3], off

.LBB0_1224:
	s_or_b64 exec, exec, s[16:17]
	v_lshlrev_b64 v[90:91], 8, v[18:19]
	v_lshlrev_b64 v[90:91], 1, v[90:91]
	s_waitcnt vmcnt(3)
	v_and_b32_e32 v99, 0xffff0000, v93
	v_lshlrev_b32_e32 v98, 16, v93
	v_and_b32_e32 v115, 0xffff0000, v92
	v_lshlrev_b32_e32 v114, 16, v92
	v_lshl_add_u64 v[92:93], v[46:47], 0, v[90:91]
	v_and_b32_e32 v103, 0xffff0000, v95
	v_lshlrev_b32_e32 v102, 16, v95
	v_and_b32_e32 v113, 0xffff0000, v94
	v_lshlrev_b32_e32 v112, 16, v94
	v_lshl_add_u64 v[90:91], v[48:49], 0, v[90:91]
	global_load_dwordx2 v[92:93], v[92:93], off
	s_nop 0
	global_load_dwordx2 v[94:95], v[90:91], off
	v_lshlrev_b64 v[122:123], 10, v[18:19]
	v_and_b32_e32 v109, 0xffff0000, v85
	v_lshlrev_b32_e32 v108, 16, v85
	v_and_b32_e32 v119, 0xffff0000, v84
	v_lshlrev_b32_e32 v118, 16, v84
	s_waitcnt vmcnt(2)
	v_lshlrev_b32_e32 v89, 16, v125
	v_lshlrev_b32_e32 v88, 16, v124
	v_and_b32_e32 v85, 0xffff0000, v125
	v_and_b32_e32 v84, 0xffff0000, v124
	v_lshl_add_u64 v[122:123], v[122:123], 1, v[54:55]
	v_and_b32_e32 v111, 0xffff0000, v104
	v_lshlrev_b32_e32 v110, 16, v104
	v_lshlrev_b64 v[130:131], 2, v[50:51]
	v_pk_add_f32 v[112:113], v[112:113], v[114:115] neg_lo:[0,1] neg_hi:[0,1]
	v_pk_add_f32 v[110:111], v[110:111], v[114:115] neg_lo:[0,1] neg_hi:[0,1]
	v_pk_fma_f32 v[14:15], v[112:113], v[14:15], v[114:115]
	v_and_b32_e32 v121, 0xffff0000, v86
	v_pk_fma_f32 v[10:11], v[110:111], v[10:11], v[14:15]
	v_lshlrev_b32_e32 v120, 16, v86
	v_and_b32_e32 v117, 0xffff0000, v82
	v_lshlrev_b32_e32 v116, 16, v82
	v_pk_add_f32 v[14:15], v[118:119], v[120:121] neg_lo:[0,1] neg_hi:[0,1]
	v_and_b32_e32 v101, 0xffff0000, v105
	v_pk_fma_f32 v[6:7], v[14:15], v[6:7], v[120:121]
	v_pk_add_f32 v[14:15], v[116:117], v[120:121] neg_lo:[0,1] neg_hi:[0,1]
	v_lshlrev_b32_e32 v100, 16, v105
	v_and_b32_e32 v105, 0xffff0000, v87
	v_lshlrev_b32_e32 v104, 16, v87
	v_lshlrev_b32_e32 v86, 16, v126
	v_and_b32_e32 v81, 0xffff0000, v127
	v_and_b32_e32 v80, 0xffff0000, v126
	v_lshlrev_b32_e32 v87, 16, v127
	v_pk_fma_f32 v[2:3], v[14:15], v[2:3], v[6:7]
	v_and_b32_e32 v107, 0xffff0000, v83
	v_lshlrev_b32_e32 v106, 16, v83
	v_and_b32_e32 v83, 0xffff0000, v97
	v_and_b32_e32 v82, 0xffff0000, v96
	s_waitcnt vmcnt(1)
	v_lshlrev_b32_e32 v91, 16, v93
	v_lshlrev_b32_e32 v90, 16, v92
	s_waitcnt vmcnt(0)
	v_lshlrev_b32_e32 v125, 16, v95
	v_lshlrev_b32_e32 v124, 16, v94
	v_pk_add_f32 v[90:91], v[90:91], v[124:125]
	global_load_dwordx2 v[124:125], v[122:123], off offset:512
	s_nop 0
	global_load_dwordx2 v[122:123], v[122:123], off offset:1536
	s_load_dwordx8 s[44:51], s[52:53], 0x108
	v_and_b32_e32 v93, 0xffff0000, v93
	v_and_b32_e32 v92, 0xffff0000, v92
	v_and_b32_e32 v95, 0xffff0000, v95
	v_and_b32_e32 v94, 0xffff0000, v94
	s_waitcnt lgkmcnt(0)
	v_lshl_add_u64 v[132:133], s[44:45], 0, v[130:131]
	global_load_dwordx4 v[110:113], v[132:133], off
	v_lshl_add_u64 v[134:135], s[46:47], 0, v[130:131]
	global_load_dwordx4 v[114:117], v[134:135], off
	v_pk_add_f32 v[92:93], v[92:93], v[94:95]
	s_waitcnt vmcnt(3)
	v_lshlrev_b32_e32 v126, 16, v124
	v_add_f32_e32 v0, v90, v92
	v_add_f32_e32 v0, v0, v91
	v_add_f32_e32 v0, v93, v0
	v_and_b32_e32 v127, 0xffff0000, v124
	s_waitcnt vmcnt(2)
	v_lshlrev_b32_e32 v128, 16, v122
	v_and_b32_e32 v129, 0xffff0000, v122
	v_pk_add_f32 v[6:7], v[126:127], v[128:129]
	s_waitcnt lgkmcnt(0)
	s_nop 1
	v_add_f32_dpp v0, v0, v0 quad_perm:[1,0,3,2] row_mask:0xf bank_mask:0xf bound_ctrl:1
	v_pk_add_f32 v[6:7], v[6:7], -2.0 op_sel_hi:[1,0]
	v_lshlrev_b32_e32 v124, 16, v125
	s_waitcnt vmcnt(1)
	v_pk_fma_f32 v[6:7], v[6:7], v[110:111], 2.0 op_sel_hi:[1,1,0]
	v_and_b32_e32 v125, 0xffff0000, v125
	s_waitcnt lgkmcnt(0)
	s_nop 1
	v_add_f32_dpp v0, v0, v0 quad_perm:[2,3,0,1] row_mask:0xf bank_mask:0xf bound_ctrl:1
	v_pk_mul_f32 v[6:7], v[10:11], v[6:7]
	v_lshlrev_b32_e32 v122, 16, v123
	v_pk_mul_f32 v[2:3], v[2:3], v[6:7]
	v_pk_add_f32 v[6:7], v[100:101], v[98:99] neg_lo:[0,1] neg_hi:[0,1]
	s_waitcnt lgkmcnt(0)
	s_nop 1
	v_add_f32_dpp v0, v0, v0 row_half_mirror row_mask:0xf bank_mask:0xf bound_ctrl:1
	s_waitcnt vmcnt(0)
	v_pk_mul_f32 v[2:3], v[114:115], v[2:3]
	v_and_b32_e32 v123, 0xffff0000, v123
	s_waitcnt lgkmcnt(0)
	s_nop 1
	v_add_f32_dpp v0, v0, v0 row_mirror row_mask:0xf bank_mask:0xf bound_ctrl:1
	v_mul_f32_e32 v94, 0x3c800000, v0
	v_add_f32_e32 v0, 0, v2
	v_add_f32_e32 v0, v0, v3
	v_pk_add_f32 v[2:3], v[102:103], v[98:99] neg_lo:[0,1] neg_hi:[0,1]
	s_nop 0
	v_pk_fma_f32 v[2:3], v[2:3], v[16:17], v[98:99]
	global_load_dwordx4 v[14:17], v[44:45], off
	v_pk_fma_f32 v[2:3], v[6:7], v[12:13], v[2:3]
	v_pk_add_f32 v[6:7], v[108:109], v[104:105] neg_lo:[0,1] neg_hi:[0,1]
	s_nop 0
	v_pk_fma_f32 v[6:7], v[6:7], v[8:9], v[104:105]
	v_pk_add_f32 v[8:9], v[106:107], v[104:105] neg_lo:[0,1] neg_hi:[0,1]
	s_nop 0
	v_pk_fma_f32 v[4:5], v[8:9], v[4:5], v[6:7]
	global_load_dwordx4 v[8:11], v[36:37], off offset:2048
	v_pk_add_f32 v[6:7], v[124:125], v[122:123]
	s_waitcnt vmcnt(0)
	v_mov_b32_e32 v12, v8
	v_pk_add_f32 v[6:7], v[6:7], -2.0 op_sel_hi:[1,0]
	v_mov_b32_e32 v13, v10
	v_pk_fma_f32 v[6:7], v[6:7], v[112:113], 2.0 op_sel_hi:[1,1,0]
	v_mov_b32_e32 v10, v9
	v_pk_mul_f32 v[2:3], v[2:3], v[6:7]
	v_pk_add_f32 v[8:9], v[84:85], v[80:81] neg_lo:[0,1] neg_hi:[0,1]
	v_pk_mul_f32 v[2:3], v[4:5], v[2:3]
	v_lshlrev_b32_e32 v5, 16, v97
	v_lshlrev_b32_e32 v4, 16, v96
	v_pk_add_f32 v[4:5], v[4:5], v[86:87] neg_lo:[0,1] neg_hi:[0,1]
	v_pk_mul_f32 v[2:3], v[116:117], v[2:3]
	v_pk_fma_f32 v[4:5], v[4:5], v[12:13], v[86:87]
	v_pk_add_f32 v[12:13], v[88:89], v[86:87] neg_lo:[0,1] neg_hi:[0,1]
	v_mov_b32_e32 v86, v14
	v_mov_b32_e32 v87, v16
	v_pk_fma_f32 v[12:13], v[12:13], v[86:87], v[4:5]
	v_pk_add_f32 v[4:5], v[82:83], v[80:81] neg_lo:[0,1] neg_hi:[0,1]
	v_mov_b32_e32 v16, v15
	v_pk_fma_f32 v[4:5], v[4:5], v[10:11], v[80:81]
	v_pk_add_f32 v[14:15], v[92:93], v[94:95] op_sel_hi:[1,0] neg_lo:[0,1] neg_hi:[0,1]
	v_pk_fma_f32 v[10:11], v[8:9], v[16:17], v[4:5]
	v_pk_add_f32 v[4:5], v[90:91], v[94:95] op_sel_hi:[1,0] neg_lo:[0,1] neg_hi:[0,1]
	v_mov_b32_e32 v9, v14
	v_mov_b32_e32 v8, v4
	v_pk_mul_f32 v[8:9], v[8:9], v[8:9]
	v_mov_b32_e32 v16, v15
	v_mov_b32_e32 v17, v5
	v_pk_mul_f32 v[16:17], v[16:17], v[16:17]
	v_add_f32_e32 v8, v8, v9
	v_add_f32_e32 v8, v17, v8
	v_add_f32_e32 v8, v16, v8
	v_add_f32_e32 v0, v0, v2
	v_add_f32_e32 v0, v0, v3
	v_lshl_add_u64 v[6:7], s[50:51], 0, v[130:131]
	s_waitcnt lgkmcnt(0)
	s_nop 1
	v_add_f32_dpp v8, v8, v8 quad_perm:[1,0,3,2] row_mask:0xf bank_mask:0xf bound_ctrl:1
	s_waitcnt lgkmcnt(0)
	s_nop 1
	v_add_f32_dpp v0, v0, v0 quad_perm:[1,0,3,2] row_mask:0xf bank_mask:0xf bound_ctrl:1
	s_waitcnt lgkmcnt(0)
	s_nop 1
	v_add_f32_dpp v8, v8, v8 quad_perm:[2,3,0,1] row_mask:0xf bank_mask:0xf bound_ctrl:1
	s_waitcnt lgkmcnt(0)
	s_nop 1
	v_add_f32_dpp v0, v0, v0 quad_perm:[2,3,0,1] row_mask:0xf bank_mask:0xf bound_ctrl:1
	s_waitcnt lgkmcnt(0)
	s_nop 1
	v_add_f32_dpp v8, v8, v8 row_half_mirror row_mask:0xf bank_mask:0xf bound_ctrl:1
	s_waitcnt lgkmcnt(0)
	s_nop 1
	v_add_f32_dpp v0, v0, v0 row_half_mirror row_mask:0xf bank_mask:0xf bound_ctrl:1
	s_waitcnt lgkmcnt(0)
	s_nop 1
	v_add_f32_dpp v8, v8, v8 row_mirror row_mask:0xf bank_mask:0xf bound_ctrl:1
	v_fmamk_f32 v8, v8, 0x3c800000, v180
	v_cmp_gt_f32_e32 vcc, s27, v8
	v_mul_f32_e32 v9, 0x4b800000, v8
	s_waitcnt lgkmcnt(0)
	s_nop 1
	v_add_f32_dpp v0, v0, v0 row_mirror row_mask:0xf bank_mask:0xf bound_ctrl:1
	v_cndmask_b32_e32 v8, v8, v9, vcc
	v_rsq_f32_e32 v8, v8
	v_lshl_add_u64 v[2:3], s[48:49], 0, v[130:131]
	v_mul_f32_e32 v9, 0x45800000, v8
	v_cndmask_b32_e32 v16, v8, v9, vcc
	v_pk_mul_f32 v[80:81], v[4:5], v[16:17] op_sel_hi:[1,0]
	global_load_dwordx4 v[2:5], v[2:3], off
	v_pk_mul_f32 v[14:15], v[14:15], v[16:17] op_sel_hi:[1,0]
	global_load_dwordx4 v[6:9], v[6:7], off
	s_waitcnt vmcnt(1)
	v_mov_b32_e32 v83, v4
	v_mov_b32_e32 v4, v3
	s_waitcnt vmcnt(0)
	v_mov_b32_e32 v85, v8
	v_mov_b32_e32 v8, v7
	v_mov_b32_e32 v82, v2
	v_mov_b32_e32 v84, v6
	v_pk_fma_f32 v[2:3], v[14:15], v[4:5], v[8:9]
	v_pk_fma_f32 v[80:81], v[80:81], v[82:83], v[84:85]
	v_pk_fma_f32 v[2:3], v[10:11], v[0:1], v[2:3] op_sel_hi:[1,0,1]
	v_pk_fma_f32 v[12:13], v[12:13], v[0:1], v[80:81] op_sel_hi:[1,0,1]
	v_pk_mul_f32 v[2:3], v[74:75], v[2:3]
	v_pk_mul_f32 v[12:13], v[76:77], v[12:13]
	v_and_b32_sdwa v5, v3, v177 dst_sel:DWORD dst_unused:UNUSED_PAD src0_sel:WORD_1 src1_sel:DWORD
	v_and_b32_sdwa v6, v2, v177 dst_sel:DWORD dst_unused:UNUSED_PAD src0_sel:WORD_1 src1_sel:DWORD
	v_and_b32_sdwa v0, v13, v177 dst_sel:DWORD dst_unused:UNUSED_PAD src0_sel:WORD_1 src1_sel:DWORD
	v_and_b32_sdwa v4, v12, v177 dst_sel:DWORD dst_unused:UNUSED_PAD src0_sel:WORD_1 src1_sel:DWORD
	v_add3_u32 v3, v3, v5, s28
	v_add3_u32 v2, v2, v6, s28
	v_add3_u32 v4, v12, v4, s28
	v_add3_u32 v0, v13, v0, s28
	v_and_b32_e32 v3, 0xffff0000, v3
	v_and_b32_e32 v2, 0xffff0000, v2
	v_or_b32_sdwa v3, v3, v0 dst_sel:DWORD dst_unused:UNUSED_PAD src0_sel:DWORD src1_sel:WORD_1
	v_or_b32_sdwa v2, v2, v4 dst_sel:DWORD dst_unused:UNUSED_PAD src0_sel:DWORD src1_sel:WORD_1
	global_store_dwordx2 v[78:79], v[2:3], off offset:1536
	s_or_b64 exec, exec, s[14:15]
	v_cmp_gt_i32_e32 vcc, s11, v64
	s_and_saveexec_b64 s[14:15], vcc
	s_cbranch_execnz .LBB0_1227

.LBB0_1227:
	v_ashrrev_i32_e32 v65, 31, v64
	v_lshlrev_b64 v[2:3], 9, v[64:65]
	v_lshl_add_u64 v[4:5], v[28:29], 0, v[2:3]
	v_lshl_add_u64 v[2:3], v[30:31], 0, v[2:3]
	global_load_dwordx2 v[8:9], v[4:5], off
	global_load_dwordx2 v[10:11], v[2:3], off
	v_mov_b64_e32 v[6:7], s[56:57]
	v_mad_i64_i32 v[76:77], s[6:7], v64, s24, v[6:7]
	v_mov_b32_e32 v73, v1
	s_load_dwordx2 s[6:7], s[52:53], 0xc8
	v_lshl_add_u64 v[2:3], v[76:77], 0, v[72:73]
	s_movk_i32 s2, 0x1000
	v_add_co_u32_e32 v2, vcc, s2, v2
	v_readlane_b32 s2, v255, 55
	v_readlane_b32 s3, v255, 56
	s_lshl_b64 s[12:13], s[2:3], 2
	s_waitcnt lgkmcnt(0)
	s_add_u32 s6, s6, s12
	v_addc_co_u32_e32 v3, vcc, 0, v3, vcc
	s_addc_u32 s7, s7, s13
	global_load_dwordx2 v[12:13], v[2:3], off offset:512
	v_mov_b32_e32 v67, v1
	global_load_dwordx4 v[2:5], v35, s[6:7]
	v_mad_i64_i32 v[84:85], s[6:7], v18, s24, v[6:7]
	v_lshl_add_u64 v[6:7], v[76:77], 0, v[66:67]
	global_load_dwordx2 v[82:83], v[6:7], off
	v_cmp_lt_i32_e64 s[44:45], v188, v182
	v_cmp_gt_i32_e32 vcc, s97, v18
	v_mov_b32_e32 v78, 0
	v_cndmask_b32_e64 v14, v181, v188, s[44:45]
	v_cmp_lt_i32_e64 s[44:45], v191, v182
	v_lshlrev_b32_e32 v63, 2, v14
	v_cndmask_b32_e32 v0, v252, v202, vcc
	v_cndmask_b32_e64 v15, v181, v191, s[44:45]
	v_lshlrev_b32_e32 v43, 2, v15
	v_lshlrev_b64 v[14:15], 11, v[64:65]
	v_cmp_lt_i32_e64 s[44:45], v190, v182
	v_lshl_add_u64 v[74:75], v[52:53], 0, v[14:15]
	v_and_b32_e32 v0, v0, v64
	v_cndmask_b32_e64 v16, v181, v190, s[44:45]
	v_cmp_lt_i32_e64 s[44:45], v189, v182
	v_lshlrev_b32_e32 v39, 2, v16
	v_mov_b32_e32 v80, 0
	v_cndmask_b32_e64 v17, v181, v189, s[44:45]
	v_lshlrev_b32_e32 v19, 2, v17
	v_cmp_ne_u32_e64 s[44:45], 0, v0
	s_waitcnt vmcnt(4)
	v_lshlrev_b32_e32 v7, 16, v9
	v_lshlrev_b32_e32 v6, 16, v8
	s_waitcnt vmcnt(3)
	v_lshlrev_b32_e32 v15, 16, v11
	v_lshlrev_b32_e32 v14, 16, v10
	v_and_b32_e32 v9, 0xffff0000, v9
	v_and_b32_e32 v8, 0xffff0000, v8
	v_and_b32_e32 v11, 0xffff0000, v11
	v_and_b32_e32 v10, 0xffff0000, v10
	v_pk_add_f32 v[6:7], v[6:7], v[14:15]
	v_pk_add_f32 v[8:9], v[8:9], v[10:11]
	v_mov_b32_e32 v14, v6
	v_mov_b32_e32 v15, v8
	v_mov_b32_e32 v16, v9
	v_mov_b32_e32 v17, v7
	v_pk_mul_f32 v[14:15], v[14:15], v[14:15]
	v_pk_mul_f32 v[16:17], v[16:17], v[16:17]
	v_add_f32_e32 v14, v14, v15
	v_add_f32_e32 v14, v14, v17
	v_add_f32_e32 v14, v16, v14
	s_waitcnt vmcnt(2)
	v_lshlrev_b32_e32 v11, 16, v13
	v_lshlrev_b32_e32 v10, 16, v12
	v_and_b32_e32 v13, 0xffff0000, v13
	v_and_b32_e32 v12, 0xffff0000, v12
	s_waitcnt lgkmcnt(0)
	s_nop 1
	v_add_f32_dpp v81, v14, v14 quad_perm:[1,0,3,2] row_mask:0xf bank_mask:0xf bound_ctrl:1
	s_waitcnt vmcnt(1)
	v_mov_b32_e32 v14, v2
	v_mov_b32_e32 v15, v4
	v_mul_f32_e32 v73, 0xbfb8aa3b, v10
	v_mul_f32_e32 v79, 0xbfb8aa3b, v12
	s_waitcnt lgkmcnt(0)
	s_nop 1
	v_add_f32_dpp v2, v81, v81 quad_perm:[2,3,0,1] row_mask:0xf bank_mask:0xf bound_ctrl:1
	v_mul_f32_e32 v16, 0xbfb8aa3b, v11
	v_mul_f32_e32 v17, 0xbfb8aa3b, v13
	v_exp_f32_e32 v73, v73
	v_exp_f32_e32 v79, v79
	s_waitcnt lgkmcnt(0)
	s_nop 1
	v_add_f32_dpp v2, v2, v2 row_half_mirror row_mask:0xf bank_mask:0xf bound_ctrl:1
	v_exp_f32_e32 v16, v16
	v_exp_f32_e32 v17, v17
	v_add_f32_e32 v73, 1.0, v73
	v_add_f32_e32 v79, 1.0, v79
	s_waitcnt lgkmcnt(0)
	s_nop 1
	v_add_f32_dpp v2, v2, v2 row_mirror row_mask:0xf bank_mask:0xf bound_ctrl:1
	v_fmamk_f32 v2, v2, 0x3c800000, v174
	v_mul_f32_e32 v4, 0x4b800000, v2
	v_cmp_gt_f32_e64 s[46:47], s27, v2
	v_add_f32_e32 v81, 1.0, v16
	v_add_f32_e32 v87, 1.0, v17
	v_cndmask_b32_e64 v2, v2, v4, s[46:47]
	v_rcp_f32_e32 v16, v73
	v_rcp_f32_e32 v86, v79
	v_rcp_f32_e32 v17, v81
	v_rcp_f32_e32 v87, v87
	v_rsq_f32_e32 v73, v2
	v_mov_b32_e32 v4, v3
	v_pk_mul_f32 v[2:3], v[16:17], v[10:11]
	v_pk_mul_f32 v[10:11], v[86:87], v[12:13]
	v_mul_f32_e32 v12, 0x45800000, v73
	v_cndmask_b32_e64 v12, v73, v12, s[46:47]
	v_pk_mul_f32 v[8:9], v[8:9], v[12:13] op_sel_hi:[1,0]
	v_pk_mul_f32 v[6:7], v[6:7], v[12:13] op_sel_hi:[1,0]
	v_pk_mul_f32 v[4:5], v[4:5], v[8:9]
	v_pk_mul_f32 v[6:7], v[14:15], v[6:7]
	v_pk_mul_f32 v[4:5], v[10:11], v[4:5]
	v_pk_mul_f32 v[2:3], v[2:3], v[6:7]
	v_and_b32_sdwa v8, v5, v177 dst_sel:DWORD dst_unused:UNUSED_PAD src0_sel:WORD_1 src1_sel:DWORD
	v_and_b32_sdwa v9, v4, v177 dst_sel:DWORD dst_unused:UNUSED_PAD src0_sel:WORD_1 src1_sel:DWORD
	v_and_b32_sdwa v6, v3, v177 dst_sel:DWORD dst_unused:UNUSED_PAD src0_sel:WORD_1 src1_sel:DWORD
	v_and_b32_sdwa v7, v2, v177 dst_sel:DWORD dst_unused:UNUSED_PAD src0_sel:WORD_1 src1_sel:DWORD
	v_add3_u32 v5, v5, v8, s28
	v_add3_u32 v4, v4, v9, s28
	v_add3_u32 v2, v2, v7, s28
	v_add3_u32 v3, v3, v6, s28
	v_and_b32_e32 v5, 0xffff0000, v5
	v_and_b32_e32 v4, 0xffff0000, v4
	v_or_b32_sdwa v3, v5, v3 dst_sel:DWORD dst_unused:UNUSED_PAD src0_sel:DWORD src1_sel:WORD_1
	v_or_b32_sdwa v2, v4, v2 dst_sel:DWORD dst_unused:UNUSED_PAD src0_sel:DWORD src1_sel:WORD_1
	v_mov_b32_e32 v81, 0
	global_store_dwordx2 v[74:75], v[2:3], off offset:1024
	s_and_saveexec_b64 s[16:17], s[44:45]
	s_cbranch_execz .LBB0_1229
	v_lshl_add_u64 v[2:3], v[84:85], 0, v[66:67]
	global_load_dwordx2 v[80:81], v[2:3], off

.LBB0_1239:
	s_or_b64 exec, exec, s[16:17]
	v_lshlrev_b64 v[86:87], 8, v[64:65]
	v_lshlrev_b64 v[86:87], 1, v[86:87]
	s_waitcnt vmcnt(3)
	v_and_b32_e32 v95, 0xffff0000, v89
	v_lshlrev_b32_e32 v94, 16, v89
	v_and_b32_e32 v111, 0xffff0000, v88
	v_lshlrev_b32_e32 v110, 16, v88
	v_lshl_add_u64 v[88:89], v[46:47], 0, v[86:87]
	v_and_b32_e32 v99, 0xffff0000, v91
	v_lshlrev_b32_e32 v98, 16, v91
	v_and_b32_e32 v109, 0xffff0000, v90
	v_lshlrev_b32_e32 v108, 16, v90
	v_lshl_add_u64 v[86:87], v[48:49], 0, v[86:87]
	global_load_dwordx2 v[88:89], v[88:89], off
	s_nop 0
	global_load_dwordx2 v[90:91], v[86:87], off
	v_lshlrev_b64 v[118:119], 10, v[64:65]
	v_and_b32_e32 v105, 0xffff0000, v81
	v_lshlrev_b32_e32 v104, 16, v81
	v_and_b32_e32 v115, 0xffff0000, v80
	v_lshlrev_b32_e32 v114, 16, v80
	s_waitcnt vmcnt(2)
	v_lshlrev_b32_e32 v85, 16, v121
	v_lshlrev_b32_e32 v84, 16, v120
	v_and_b32_e32 v81, 0xffff0000, v121
	v_and_b32_e32 v80, 0xffff0000, v120
	v_lshl_add_u64 v[118:119], v[118:119], 1, v[54:55]
	v_and_b32_e32 v107, 0xffff0000, v100
	v_lshlrev_b32_e32 v106, 16, v100
	v_lshlrev_b64 v[126:127], 2, v[50:51]
	v_pk_add_f32 v[108:109], v[108:109], v[110:111] neg_lo:[0,1] neg_hi:[0,1]
	v_pk_add_f32 v[106:107], v[106:107], v[110:111] neg_lo:[0,1] neg_hi:[0,1]
	v_pk_fma_f32 v[14:15], v[108:109], v[14:15], v[110:111]
	v_and_b32_e32 v117, 0xffff0000, v82
	v_pk_fma_f32 v[10:11], v[106:107], v[10:11], v[14:15]
	v_lshlrev_b32_e32 v116, 16, v82
	v_and_b32_e32 v113, 0xffff0000, v78
	v_lshlrev_b32_e32 v112, 16, v78
	v_pk_add_f32 v[14:15], v[114:115], v[116:117] neg_lo:[0,1] neg_hi:[0,1]
	v_and_b32_e32 v97, 0xffff0000, v101
	v_pk_fma_f32 v[6:7], v[14:15], v[6:7], v[116:117]
	v_pk_add_f32 v[14:15], v[112:113], v[116:117] neg_lo:[0,1] neg_hi:[0,1]
	v_lshlrev_b32_e32 v96, 16, v101
	v_and_b32_e32 v101, 0xffff0000, v83
	v_lshlrev_b32_e32 v100, 16, v83
	v_lshlrev_b32_e32 v82, 16, v122
	v_and_b32_e32 v77, 0xffff0000, v123
	v_and_b32_e32 v76, 0xffff0000, v122
	v_lshlrev_b32_e32 v83, 16, v123
	v_pk_fma_f32 v[2:3], v[14:15], v[2:3], v[6:7]
	v_and_b32_e32 v103, 0xffff0000, v79
	v_lshlrev_b32_e32 v102, 16, v79
	v_and_b32_e32 v79, 0xffff0000, v93
	v_and_b32_e32 v78, 0xffff0000, v92
	s_waitcnt vmcnt(1)
	v_lshlrev_b32_e32 v87, 16, v89
	v_lshlrev_b32_e32 v86, 16, v88
	s_waitcnt vmcnt(0)
	v_lshlrev_b32_e32 v121, 16, v91
	v_lshlrev_b32_e32 v120, 16, v90
	v_pk_add_f32 v[86:87], v[86:87], v[120:121]
	global_load_dwordx2 v[120:121], v[118:119], off offset:512
	s_nop 0
	global_load_dwordx2 v[118:119], v[118:119], off offset:1536
	s_load_dwordx8 s[44:51], s[52:53], 0x108
	v_and_b32_e32 v89, 0xffff0000, v89
	v_and_b32_e32 v88, 0xffff0000, v88
	v_and_b32_e32 v91, 0xffff0000, v91
	v_and_b32_e32 v90, 0xffff0000, v90
	s_waitcnt lgkmcnt(0)
	v_lshl_add_u64 v[128:129], s[44:45], 0, v[126:127]
	global_load_dwordx4 v[106:109], v[128:129], off
	v_lshl_add_u64 v[130:131], s[46:47], 0, v[126:127]
	global_load_dwordx4 v[110:113], v[130:131], off
	v_pk_add_f32 v[88:89], v[88:89], v[90:91]
	s_waitcnt vmcnt(3)
	v_lshlrev_b32_e32 v122, 16, v120
	v_add_f32_e32 v0, v86, v88
	v_add_f32_e32 v0, v0, v87
	v_add_f32_e32 v0, v89, v0
	v_and_b32_e32 v123, 0xffff0000, v120
	s_waitcnt vmcnt(2)
	v_lshlrev_b32_e32 v124, 16, v118
	v_and_b32_e32 v125, 0xffff0000, v118
	v_pk_add_f32 v[6:7], v[122:123], v[124:125]
	s_waitcnt lgkmcnt(0)
	s_nop 1
	v_add_f32_dpp v0, v0, v0 quad_perm:[1,0,3,2] row_mask:0xf bank_mask:0xf bound_ctrl:1
	v_pk_add_f32 v[6:7], v[6:7], -2.0 op_sel_hi:[1,0]
	v_lshlrev_b32_e32 v120, 16, v121
	s_waitcnt vmcnt(1)
	v_pk_fma_f32 v[6:7], v[6:7], v[106:107], 2.0 op_sel_hi:[1,1,0]
	v_and_b32_e32 v121, 0xffff0000, v121
	s_waitcnt lgkmcnt(0)
	s_nop 1
	v_add_f32_dpp v0, v0, v0 quad_perm:[2,3,0,1] row_mask:0xf bank_mask:0xf bound_ctrl:1
	v_pk_mul_f32 v[6:7], v[10:11], v[6:7]
	v_lshlrev_b32_e32 v118, 16, v119
	v_pk_mul_f32 v[2:3], v[2:3], v[6:7]
	v_pk_add_f32 v[6:7], v[96:97], v[94:95] neg_lo:[0,1] neg_hi:[0,1]
	s_waitcnt lgkmcnt(0)
	s_nop 1
	v_add_f32_dpp v0, v0, v0 row_half_mirror row_mask:0xf bank_mask:0xf bound_ctrl:1
	s_waitcnt vmcnt(0)
	v_pk_mul_f32 v[2:3], v[110:111], v[2:3]
	v_and_b32_e32 v119, 0xffff0000, v119
	s_waitcnt lgkmcnt(0)
	s_nop 1
	v_add_f32_dpp v0, v0, v0 row_mirror row_mask:0xf bank_mask:0xf bound_ctrl:1
	v_mul_f32_e32 v90, 0x3c800000, v0
	v_add_f32_e32 v0, 0, v2
	v_add_f32_e32 v0, v0, v3
	v_pk_add_f32 v[2:3], v[98:99], v[94:95] neg_lo:[0,1] neg_hi:[0,1]
	s_nop 0
	v_pk_fma_f32 v[2:3], v[2:3], v[16:17], v[94:95]
	global_load_dwordx4 v[14:17], v[44:45], off
	v_pk_fma_f32 v[2:3], v[6:7], v[12:13], v[2:3]
	v_pk_add_f32 v[6:7], v[104:105], v[100:101] neg_lo:[0,1] neg_hi:[0,1]
	s_nop 0
	v_pk_fma_f32 v[6:7], v[6:7], v[8:9], v[100:101]
	v_pk_add_f32 v[8:9], v[102:103], v[100:101] neg_lo:[0,1] neg_hi:[0,1]
	s_nop 0
	v_pk_fma_f32 v[4:5], v[8:9], v[4:5], v[6:7]
	global_load_dwordx4 v[8:11], v[36:37], off offset:2048
	v_pk_add_f32 v[6:7], v[120:121], v[118:119]
	s_waitcnt vmcnt(0)
	v_mov_b32_e32 v12, v8
	v_pk_add_f32 v[6:7], v[6:7], -2.0 op_sel_hi:[1,0]
	v_mov_b32_e32 v13, v10
	v_pk_fma_f32 v[6:7], v[6:7], v[108:109], 2.0 op_sel_hi:[1,1,0]
	v_mov_b32_e32 v10, v9
	v_pk_mul_f32 v[2:3], v[2:3], v[6:7]
	v_pk_add_f32 v[8:9], v[80:81], v[76:77] neg_lo:[0,1] neg_hi:[0,1]
	v_pk_mul_f32 v[2:3], v[4:5], v[2:3]
	v_lshlrev_b32_e32 v5, 16, v93
	v_lshlrev_b32_e32 v4, 16, v92
	v_pk_add_f32 v[4:5], v[4:5], v[82:83] neg_lo:[0,1] neg_hi:[0,1]
	v_pk_mul_f32 v[2:3], v[112:113], v[2:3]
	v_pk_fma_f32 v[4:5], v[4:5], v[12:13], v[82:83]
	v_pk_add_f32 v[12:13], v[84:85], v[82:83] neg_lo:[0,1] neg_hi:[0,1]
	v_mov_b32_e32 v82, v14
	v_mov_b32_e32 v83, v16
	v_pk_fma_f32 v[12:13], v[12:13], v[82:83], v[4:5]
	v_pk_add_f32 v[4:5], v[78:79], v[76:77] neg_lo:[0,1] neg_hi:[0,1]
	v_mov_b32_e32 v16, v15
	v_pk_fma_f32 v[4:5], v[4:5], v[10:11], v[76:77]
	v_pk_add_f32 v[14:15], v[88:89], v[90:91] op_sel_hi:[1,0] neg_lo:[0,1] neg_hi:[0,1]
	v_pk_fma_f32 v[10:11], v[8:9], v[16:17], v[4:5]
	v_pk_add_f32 v[4:5], v[86:87], v[90:91] op_sel_hi:[1,0] neg_lo:[0,1] neg_hi:[0,1]
	v_mov_b32_e32 v9, v14
	v_mov_b32_e32 v8, v4
	v_pk_mul_f32 v[8:9], v[8:9], v[8:9]
	v_mov_b32_e32 v16, v15
	v_mov_b32_e32 v17, v5
	v_pk_mul_f32 v[16:17], v[16:17], v[16:17]
	v_add_f32_e32 v8, v8, v9
	v_add_f32_e32 v8, v17, v8
	v_add_f32_e32 v8, v16, v8
	v_add_f32_e32 v0, v0, v2
	v_add_f32_e32 v0, v0, v3
	v_lshl_add_u64 v[6:7], s[50:51], 0, v[126:127]
	s_waitcnt lgkmcnt(0)
	s_nop 1
	v_add_f32_dpp v8, v8, v8 quad_perm:[1,0,3,2] row_mask:0xf bank_mask:0xf bound_ctrl:1
	s_waitcnt lgkmcnt(0)
	s_nop 1
	v_add_f32_dpp v0, v0, v0 quad_perm:[1,0,3,2] row_mask:0xf bank_mask:0xf bound_ctrl:1
	s_waitcnt lgkmcnt(0)
	s_nop 1
	v_add_f32_dpp v8, v8, v8 quad_perm:[2,3,0,1] row_mask:0xf bank_mask:0xf bound_ctrl:1
	s_waitcnt lgkmcnt(0)
	s_nop 1
	v_add_f32_dpp v0, v0, v0 quad_perm:[2,3,0,1] row_mask:0xf bank_mask:0xf bound_ctrl:1
	s_waitcnt lgkmcnt(0)
	s_nop 1
	v_add_f32_dpp v8, v8, v8 row_half_mirror row_mask:0xf bank_mask:0xf bound_ctrl:1
	s_waitcnt lgkmcnt(0)
	s_nop 1
	v_add_f32_dpp v0, v0, v0 row_half_mirror row_mask:0xf bank_mask:0xf bound_ctrl:1
	s_waitcnt lgkmcnt(0)
	s_nop 1
	v_add_f32_dpp v8, v8, v8 row_mirror row_mask:0xf bank_mask:0xf bound_ctrl:1
	v_fmamk_f32 v8, v8, 0x3c800000, v180
	v_cmp_gt_f32_e32 vcc, s27, v8
	v_mul_f32_e32 v9, 0x4b800000, v8
	s_waitcnt lgkmcnt(0)
	s_nop 1
	v_add_f32_dpp v0, v0, v0 row_mirror row_mask:0xf bank_mask:0xf bound_ctrl:1
	v_cndmask_b32_e32 v8, v8, v9, vcc
	v_rsq_f32_e32 v8, v8
	v_lshl_add_u64 v[2:3], s[48:49], 0, v[126:127]
	v_mul_f32_e32 v9, 0x45800000, v8
	v_cndmask_b32_e32 v16, v8, v9, vcc
	v_pk_mul_f32 v[76:77], v[4:5], v[16:17] op_sel_hi:[1,0]
	global_load_dwordx4 v[2:5], v[2:3], off
	v_pk_mul_f32 v[14:15], v[14:15], v[16:17] op_sel_hi:[1,0]
	global_load_dwordx4 v[6:9], v[6:7], off
	s_waitcnt vmcnt(1)
	v_mov_b32_e32 v79, v4
	v_mov_b32_e32 v4, v3
	s_waitcnt vmcnt(0)
	v_mov_b32_e32 v81, v8
	v_mov_b32_e32 v8, v7
	v_mov_b32_e32 v78, v2
	v_mov_b32_e32 v80, v6
	v_pk_fma_f32 v[2:3], v[14:15], v[4:5], v[8:9]
	v_pk_fma_f32 v[76:77], v[76:77], v[78:79], v[80:81]
	v_pk_fma_f32 v[2:3], v[10:11], v[0:1], v[2:3] op_sel_hi:[1,0,1]
	v_pk_fma_f32 v[12:13], v[12:13], v[0:1], v[76:77] op_sel_hi:[1,0,1]
	v_pk_mul_f32 v[2:3], v[68:69], v[2:3]
	v_pk_mul_f32 v[12:13], v[70:71], v[12:13]
	v_and_b32_sdwa v5, v3, v177 dst_sel:DWORD dst_unused:UNUSED_PAD src0_sel:WORD_1 src1_sel:DWORD
	v_and_b32_sdwa v6, v2, v177 dst_sel:DWORD dst_unused:UNUSED_PAD src0_sel:WORD_1 src1_sel:DWORD
	v_and_b32_sdwa v0, v13, v177 dst_sel:DWORD dst_unused:UNUSED_PAD src0_sel:WORD_1 src1_sel:DWORD
	v_and_b32_sdwa v4, v12, v177 dst_sel:DWORD dst_unused:UNUSED_PAD src0_sel:WORD_1 src1_sel:DWORD
	v_add3_u32 v3, v3, v5, s28
	v_add3_u32 v2, v2, v6, s28
	v_add3_u32 v4, v12, v4, s28
	v_add3_u32 v0, v13, v0, s28
	v_and_b32_e32 v3, 0xffff0000, v3
	v_and_b32_e32 v2, 0xffff0000, v2
	v_or_b32_sdwa v3, v3, v0 dst_sel:DWORD dst_unused:UNUSED_PAD src0_sel:DWORD src1_sel:WORD_1
	v_or_b32_sdwa v2, v2, v4 dst_sel:DWORD dst_unused:UNUSED_PAD src0_sel:DWORD src1_sel:WORD_1
	global_store_dwordx2 v[74:75], v[2:3], off offset:1536
	s_or_b64 exec, exec, s[14:15]
	v_cmp_gt_i32_e32 vcc, s11, v62
	s_and_saveexec_b64 s[14:15], vcc
	s_cbranch_execz .LBB0_1196
.LBB0_1240:
	v_ashrrev_i32_e32 v63, 31, v62
	v_lshlrev_b64 v[2:3], 9, v[62:63]
	v_lshl_add_u64 v[4:5], v[28:29], 0, v[2:3]
	v_lshl_add_u64 v[2:3], v[30:31], 0, v[2:3]
	global_load_dwordx2 v[8:9], v[4:5], off
	global_load_dwordx2 v[10:11], v[2:3], off
	v_mov_b64_e32 v[6:7], s[56:57]
	v_mad_i64_i32 v[68:69], s[6:7], v62, s24, v[6:7]
	v_mov_b32_e32 v73, v1
	s_load_dwordx2 s[6:7], s[52:53], 0xc8
	v_lshl_add_u64 v[2:3], v[68:69], 0, v[72:73]
	s_movk_i32 s2, 0x1000
	v_add_co_u32_e32 v2, vcc, s2, v2
	v_readlane_b32 s2, v255, 55
	v_readlane_b32 s3, v255, 56
	s_lshl_b64 s[12:13], s[2:3], 2
	s_waitcnt lgkmcnt(0)
	s_add_u32 s6, s6, s12
	v_addc_co_u32_e32 v3, vcc, 0, v3, vcc
	s_addc_u32 s7, s7, s13
	global_load_dwordx2 v[12:13], v[2:3], off offset:512
	v_mov_b32_e32 v67, v1
	global_load_dwordx4 v[2:5], v35, s[6:7]
	v_mad_i64_i32 v[76:77], s[6:7], v64, s24, v[6:7]
	v_lshl_add_u64 v[6:7], v[68:69], 0, v[66:67]
	global_load_dwordx2 v[74:75], v[6:7], off
	v_cmp_lt_i32_e64 s[44:45], v188, v182
	s_movk_i32 s2, 0x3ffe
	v_cmp_gt_i32_e32 vcc, s2, v18
	v_cndmask_b32_e64 v14, v181, v188, s[44:45]
	v_cmp_lt_i32_e64 s[44:45], v191, v182
	v_lshlrev_b32_e32 v43, 2, v14
	v_cndmask_b32_e32 v0, v252, v202, vcc
	v_cndmask_b32_e64 v15, v181, v191, s[44:45]
	v_lshlrev_b32_e32 v39, 2, v15
	v_lshlrev_b64 v[14:15], 11, v[62:63]
	v_cmp_lt_i32_e64 s[44:45], v190, v182
	v_lshl_add_u64 v[64:65], v[52:53], 0, v[14:15]
	v_and_b32_e32 v0, v0, v62
	v_cndmask_b32_e64 v16, v181, v190, s[44:45]
	v_cmp_lt_i32_e64 s[44:45], v189, v182
	v_lshlrev_b32_e32 v35, 2, v16
	v_mov_b32_e32 v70, 0
	v_cndmask_b32_e64 v17, v181, v189, s[44:45]
	v_lshlrev_b32_e32 v19, 2, v17
	v_mov_b32_e32 v72, 0
	v_cmp_ne_u32_e64 s[44:45], 0, v0
	s_waitcnt vmcnt(4)
	v_lshlrev_b32_e32 v7, 16, v9
	v_lshlrev_b32_e32 v6, 16, v8
	s_waitcnt vmcnt(3)
	v_lshlrev_b32_e32 v15, 16, v11
	v_lshlrev_b32_e32 v14, 16, v10
	v_and_b32_e32 v9, 0xffff0000, v9
	v_and_b32_e32 v8, 0xffff0000, v8
	v_and_b32_e32 v11, 0xffff0000, v11
	v_and_b32_e32 v10, 0xffff0000, v10
	v_pk_add_f32 v[6:7], v[6:7], v[14:15]
	v_pk_add_f32 v[8:9], v[8:9], v[10:11]
	v_mov_b32_e32 v14, v6
	v_mov_b32_e32 v15, v8
	v_mov_b32_e32 v16, v9
	v_mov_b32_e32 v17, v7
	v_pk_mul_f32 v[14:15], v[14:15], v[14:15]
	v_pk_mul_f32 v[16:17], v[16:17], v[16:17]
	v_add_f32_e32 v14, v14, v15
	v_add_f32_e32 v14, v14, v17
	v_add_f32_e32 v14, v16, v14
	s_waitcnt vmcnt(2)
	v_lshlrev_b32_e32 v11, 16, v13
	v_lshlrev_b32_e32 v10, 16, v12
	v_and_b32_e32 v13, 0xffff0000, v13
	v_and_b32_e32 v12, 0xffff0000, v12
	s_waitcnt lgkmcnt(0)
	s_nop 1
	v_add_f32_dpp v78, v14, v14 quad_perm:[1,0,3,2] row_mask:0xf bank_mask:0xf bound_ctrl:1
	s_waitcnt vmcnt(1)
	v_mov_b32_e32 v14, v2
	v_mov_b32_e32 v15, v4
	v_mul_f32_e32 v71, 0xbfb8aa3b, v10
	v_mul_f32_e32 v73, 0xbfb8aa3b, v12
	s_waitcnt lgkmcnt(0)
	s_nop 1
	v_add_f32_dpp v2, v78, v78 quad_perm:[2,3,0,1] row_mask:0xf bank_mask:0xf bound_ctrl:1
	v_mul_f32_e32 v16, 0xbfb8aa3b, v11
	v_mul_f32_e32 v17, 0xbfb8aa3b, v13
	v_exp_f32_e32 v71, v71
	v_exp_f32_e32 v73, v73
	s_waitcnt lgkmcnt(0)
	s_nop 1
	v_add_f32_dpp v2, v2, v2 row_half_mirror row_mask:0xf bank_mask:0xf bound_ctrl:1
	v_exp_f32_e32 v16, v16
	v_exp_f32_e32 v17, v17
	v_add_f32_e32 v71, 1.0, v71
	v_add_f32_e32 v73, 1.0, v73
	s_waitcnt lgkmcnt(0)
	s_nop 1
	v_add_f32_dpp v2, v2, v2 row_mirror row_mask:0xf bank_mask:0xf bound_ctrl:1
	v_fmamk_f32 v2, v2, 0x3c800000, v174
	v_mul_f32_e32 v4, 0x4b800000, v2
	v_cmp_gt_f32_e64 s[46:47], s27, v2
	v_add_f32_e32 v79, 1.0, v16
	v_add_f32_e32 v80, 1.0, v17
	v_cndmask_b32_e64 v2, v2, v4, s[46:47]
	v_rcp_f32_e32 v16, v71
	v_rcp_f32_e32 v78, v73
	v_rcp_f32_e32 v17, v79
	v_rcp_f32_e32 v79, v80
	v_rsq_f32_e32 v71, v2
	v_mov_b32_e32 v4, v3
	v_pk_mul_f32 v[2:3], v[16:17], v[10:11]
	v_pk_mul_f32 v[10:11], v[78:79], v[12:13]
	v_mul_f32_e32 v12, 0x45800000, v71
	v_cndmask_b32_e64 v12, v71, v12, s[46:47]
	v_pk_mul_f32 v[8:9], v[8:9], v[12:13] op_sel_hi:[1,0]
	v_pk_mul_f32 v[6:7], v[6:7], v[12:13] op_sel_hi:[1,0]
	v_pk_mul_f32 v[4:5], v[4:5], v[8:9]
	v_pk_mul_f32 v[6:7], v[14:15], v[6:7]
	v_pk_mul_f32 v[4:5], v[10:11], v[4:5]
	v_pk_mul_f32 v[2:3], v[2:3], v[6:7]
	v_and_b32_sdwa v8, v5, v177 dst_sel:DWORD dst_unused:UNUSED_PAD src0_sel:WORD_1 src1_sel:DWORD
	v_and_b32_sdwa v9, v4, v177 dst_sel:DWORD dst_unused:UNUSED_PAD src0_sel:WORD_1 src1_sel:DWORD
	v_and_b32_sdwa v6, v3, v177 dst_sel:DWORD dst_unused:UNUSED_PAD src0_sel:WORD_1 src1_sel:DWORD
	v_and_b32_sdwa v7, v2, v177 dst_sel:DWORD dst_unused:UNUSED_PAD src0_sel:WORD_1 src1_sel:DWORD
	v_add3_u32 v5, v5, v8, s28
	v_add3_u32 v4, v4, v9, s28
	v_add3_u32 v2, v2, v7, s28
	v_add3_u32 v3, v3, v6, s28
	v_and_b32_e32 v5, 0xffff0000, v5
	v_and_b32_e32 v4, 0xffff0000, v4
	v_or_b32_sdwa v3, v5, v3 dst_sel:DWORD dst_unused:UNUSED_PAD src0_sel:DWORD src1_sel:WORD_1
	v_or_b32_sdwa v2, v4, v2 dst_sel:DWORD dst_unused:UNUSED_PAD src0_sel:DWORD src1_sel:WORD_1
	v_mov_b32_e32 v73, 0
	global_store_dwordx2 v[64:65], v[2:3], off offset:1024
	s_and_saveexec_b64 s[16:17], s[44:45]
	s_cbranch_execz .LBB0_1242
	v_lshl_add_u64 v[2:3], v[76:77], 0, v[66:67]
	global_load_dwordx2 v[72:73], v[2:3], off
